# DSA P.V loop head: 16 dead v_mov_b64 (copy of current V rows into registers the next gathers overwrite) removed, single wait kept
# speedup vs baseline: 1.0207x; 1.0081x over previous
.LBB0_278:
	s_andn2_b64 vcc, exec, s[42:43]
	s_waitcnt vmcnt(0)
	s_cbranch_vccnz .LBB0_275
	v_min_i32_e32 v14, s50, v105
	v_add_u32_e32 v15, 36, v103
	v_add_u32_e32 v16, 40, v103
	v_add_u32_e32 v17, 44, v103
	v_add_u32_e32 v18, 48, v103
	v_add_u32_e32 v19, 52, v103
	v_add_u32_e32 v20, 56, v103
	v_add_u32_e32 v21, 60, v103
	v_lshl_add_u32 v14, v14, 1, s51
	v_min_i32_e32 v15, s50, v15
	v_min_i32_e32 v16, s50, v16
	v_min_i32_e32 v17, s50, v17
	v_min_i32_e32 v18, s50, v18
	v_min_i32_e32 v19, s50, v19
	v_min_i32_e32 v20, s50, v20
	v_min_i32_e32 v21, s50, v21
	v_lshl_add_u32 v15, v15, 1, s51
	v_lshl_add_u32 v16, v16, 1, s51
	v_lshl_add_u32 v17, v17, 1, s51
	v_lshl_add_u32 v18, v18, 1, s51
	v_lshl_add_u32 v19, v19, 1, s51
	v_lshl_add_u32 v20, v20, 1, s51
	v_lshl_add_u32 v21, v21, 1, s51
	ds_read_u16 v14, v14
	ds_read_u16 v22, v15
	ds_read_u16 v23, v16
	ds_read_u16 v24, v17
	ds_read_u16 v30, v18
	ds_read_u16 v32, v19
	ds_read_u16 v38, v20
	ds_read_u16 v40, v21
	s_waitcnt lgkmcnt(7)
	v_lshlrev_b32_e32 v150, 9, v14
	v_lshl_add_u64 v[14:15], v[162:163], 0, v[150:151]
	s_waitcnt lgkmcnt(6)
	v_lshlrev_b32_e32 v150, 9, v22
	v_lshl_add_u64 v[18:19], v[162:163], 0, v[150:151]
	s_waitcnt lgkmcnt(5)
	v_lshlrev_b32_e32 v150, 9, v23
	v_lshl_add_u64 v[22:23], v[162:163], 0, v[150:151]
	s_waitcnt lgkmcnt(4)
	v_lshlrev_b32_e32 v150, 9, v24
	v_lshl_add_u64 v[26:27], v[162:163], 0, v[150:151]
	s_waitcnt lgkmcnt(3)
	v_lshlrev_b32_e32 v150, 9, v30
	v_lshl_add_u64 v[30:31], v[162:163], 0, v[150:151]
	s_waitcnt lgkmcnt(2)
	v_lshlrev_b32_e32 v150, 9, v32
	v_lshl_add_u64 v[34:35], v[162:163], 0, v[150:151]
	s_waitcnt lgkmcnt(1)
	v_lshlrev_b32_e32 v150, 9, v38
	v_lshl_add_u64 v[38:39], v[162:163], 0, v[150:151]
	s_waitcnt lgkmcnt(0)
	v_lshlrev_b32_e32 v150, 9, v40
	v_lshl_add_u64 v[42:43], v[162:163], 0, v[150:151]
	global_load_dwordx4 v[14:17], v[14:15], off offset:256
	s_nop 0
	global_load_dwordx4 v[18:21], v[18:19], off offset:256
	s_nop 0
	global_load_dwordx4 v[22:25], v[22:23], off offset:256
	s_nop 0
	global_load_dwordx4 v[26:29], v[26:27], off offset:256
	s_nop 0
	global_load_dwordx4 v[30:33], v[30:31], off offset:256
	s_nop 0
	global_load_dwordx4 v[34:37], v[34:35], off offset:256
	s_nop 0
	global_load_dwordx4 v[38:41], v[38:39], off offset:256
	s_nop 0
	global_load_dwordx4 v[42:45], v[42:43], off offset:256
	v_mov_b32_e32 v104, v105
	s_branch .LBB0_275
